# mixer: next-pair claim atomic issued when the current item enters its last tile/chunk (ctx attention, ctx scans), consumed at the claim site
# baseline (speedup 1.0000x reference)
.LBB0_230:
	v_mov_b32_e32 v249, 0
	s_cmpk_gt_i32 s4, 0x27f
	s_mov_b64 s[0:1], -1
	s_cbranch_scc1 .LBB0_229
	s_lshl_b32 s82, s4, 1
	s_add_i32 s82, s82, s77
	s_cmpk_gt_i32 s82, 0x7f
	s_cbranch_scc0 .LBB0_429
	s_cmpk_gt_u32 s82, 0x27f
	s_cbranch_scc0 .LBB0_411
	s_cmpk_gt_u32 s82, 0x2bf
	s_cbranch_scc0 .LBB0_338
	s_cmpk_gt_u32 s82, 0x2ff
	s_cbranch_scc0 .LBB0_248
	s_cmpk_gt_u32 s82, 0x3ff
	s_cbranch_scc0 .LBB0_241
	s_lshl_b32 s0, s82, 5
	s_add_i32 s0, s0, 0x7fff8000
	v_mov_b32 v0, 0
	s_and_b32 s6, s0, 0x7fffff00
	v_add_u32_sdwa v8, v0, v160 dst_sel:DWORD dst_unused:UNUSED_PAD src0_sel:DWORD src1_sel:BYTE_0
	v_readlane_b32 s0, v254, 59
	v_and_b32_e32 v9, 31, v8
	s_or_b32 s0, s0, s6
	v_or_b32_e32 v1, s0, v9
	s_lshl_b32 s0, s82, 4
	s_bfe_u32 s5, s82, 0x20001
	s_and_b32 s7, s0, 64
	v_readlane_b32 s0, v254, 60
	s_or_b32 s0, s5, s0
	s_ashr_i32 s1, s0, 31
	v_readlane_b32 s12, v254, 14
	v_ashrrev_i32_e32 v0, 1, v8
	s_lshl_b32 s4, s5, 6
	s_or_b32 s8, s7, 0xd80
	s_lshl_b64 s[0:1], s[0:1], 2
	v_readlane_b32 s20, v254, 22
	v_and_b32_e32 v0, 0xffffffe0, v0
	v_readlane_b32 s21, v254, 23
	s_add_u32 s0, s20, s0
	v_add_u32_e32 v96, v1, v0
	s_addc_u32 s1, s21, s1
	v_mov_b64_e32 v[0:1], s[62:63]
	v_bfe_u32 v98, v8, 5, 1
	global_load_dword v99, v129, s[0:1]
	v_mad_i64_i32 v[2:3], s[0:1], v96, s87, v[0:1]
	s_lshl_b32 s92, s5, 7
	v_lshl_add_u64 v[2:3], v[2:3], 0, s[92:93]
	v_lshlrev_b32_e32 v128, 4, v98
	v_lshl_add_u64 v[2:3], v[2:3], 0, v[128:129]
	s_mov_b64 s[0:1], 0x1900
	v_ashrrev_i32_e32 v11, 2, v8
	v_lshl_add_u64 v[4:5], v[2:3], 0, s[0:1]
	s_movk_i32 s0, 0x1000
	s_or_b32 s7, s7, 0xe00
	v_add_u32_e32 v13, s6, v11
	v_add_co_u32_e32 v2, vcc, s0, v2
	v_mad_i64_i32 v[0:1], s[0:1], v13, s87, v[0:1]
	s_lshl_b32 s92, s7, 1
	v_and_b32_e32 v12, 3, v8
	v_lshl_add_u64 v[6:7], v[0:1], 0, s[92:93]
	s_lshl_b32 s92, s8, 1
	v_lshlrev_b32_e32 v128, 5, v12
	v_lshl_add_u64 v[0:1], v[0:1], 0, s[92:93]
	v_lshl_add_u64 v[0:1], v[0:1], 0, v[128:129]
	v_addc_co_u32_e32 v3, vcc, 0, v3, vcc
	global_load_dwordx4 v[64:67], v[4:5], off offset:32
	global_load_dwordx4 v[68:71], v[4:5], off offset:64
	v_lshl_add_u64 v[6:7], v[6:7], 0, v[128:129]
	global_load_dwordx4 v[40:43], v[0:1], off offset:16
	global_load_dwordx4 v[44:47], v[0:1], off
	s_waitcnt lgkmcnt(0)
	global_load_dwordx4 v[32:35], v[6:7], off offset:16
	global_load_dwordx4 v[36:39], v[6:7], off
	global_load_dwordx4 v[72:75], v[2:3], off offset:2304
	global_load_dwordx4 v[76:79], v[4:5], off offset:96
	v_lshrrev_b32_e32 v1, 3, v8
	v_bfe_u32 v2, v8, 3, 3
	v_lshlrev_b32_e32 v4, 1, v12
	v_lshrrev_b32_e32 v10, 5, v8
	v_bitop3_b32 v1, v4, v1, 7 bitop3:0x78
	v_bitop3_b32 v2, v4, v2, 1 bitop3:0x36
	v_bfe_u32 v4, v8, 1, 3
	v_mul_u32_u24_e32 v8, 0x440, v12
	v_lshl_add_u32 v5, v9, 7, s78
	v_mul_u32_u24_e32 v7, 0x88, v9
	v_lshlrev_b32_e32 v8, 1, v8
	v_lshlrev_b32_e32 v9, 1, v11
	s_movk_i32 s0, 0xff82
	v_lshl_add_u32 v3, v11, 7, s78
	v_cmp_lt_i32_e32 vcc, v168, v167
	v_add3_u32 v101, s78, v8, v9
	v_mul_lo_u32 v9, v11, s0
	v_cndmask_b32_e32 v6, v165, v168, vcc
	v_add3_u32 v102, v3, v9, v8
	v_bitop3_b32 v8, v10, v4, 1 bitop3:0x6c
	v_bitop3_b32 v9, v98, v4, 2 bitop3:0x36
	v_bitop3_b32 v10, v98, v4, 4 bitop3:0x36
	v_bitop3_b32 v4, v98, v4, 6 bitop3:0x36
	v_lshlrev_b32_e32 v0, 4, v12
	v_lshlrev_b32_e32 v1, 4, v1
	v_lshlrev_b32_e32 v2, 4, v2
	v_lshlrev_b32_e32 v100, 2, v6
	v_lshl_add_u32 v6, v98, 3, s78
	v_lshlrev_b32_e32 v8, 4, v8
	v_lshlrev_b32_e32 v9, 4, v9
	v_lshlrev_b32_e32 v10, 4, v10
	v_lshlrev_b32_e32 v4, 4, v4
	v_mov_b32_e32 v105, 0
	v_ashrrev_i32_e32 v97, 31, v96
	s_mov_b32 s5, 0
	v_add_u32_e32 v103, 64, v13
	v_mov_b32_e32 v112, 0xf149f2ca
	s_lshl_b32 s92, s7, 1
	v_lshlrev_b32_e32 v128, 1, v0
	s_lshl_b32 s0, s8, 1
	v_add_u32_e32 v104, v3, v1
	v_add_u32_e32 v106, v3, v2
	v_add_u32_e32 v107, v5, v8
	v_add_u32_e32 v108, v5, v9
	v_add_u32_e32 v109, v5, v10
	v_add_u32_e32 v110, v5, v4
	v_add_u32_e32 v111, v6, v7
	v_mov_b32_e32 v16, 0
	v_mov_b32_e32 v17, v105
	v_mov_b32_e32 v18, v105
	v_mov_b32_e32 v19, v105
	v_mov_b32_e32 v20, v105
	v_mov_b32_e32 v21, v105
	v_mov_b32_e32 v22, v105
	v_mov_b32_e32 v23, v105
	v_mov_b32_e32 v24, v105
	v_mov_b32_e32 v25, v105
	v_mov_b32_e32 v26, v105
	v_mov_b32_e32 v27, v105
	v_mov_b32_e32 v28, v105
	v_mov_b32_e32 v29, v105
	v_mov_b32_e32 v30, v105
	v_mov_b32_e32 v31, v105
	v_mov_b32_e32 v0, 0
	v_mov_b32_e32 v1, v105
	v_mov_b32_e32 v2, v105
	v_mov_b32_e32 v3, v105
	v_mov_b32_e32 v4, v105
	v_mov_b32_e32 v5, v105
	v_mov_b32_e32 v6, v105
	v_mov_b32_e32 v7, v105
	v_mov_b32_e32 v8, v105
	v_mov_b32_e32 v9, v105
	v_mov_b32_e32 v10, v105
	s_waitcnt vmcnt(0)
	v_mov_b64_e32 v[94:95], v[42:43]
	v_mov_b64_e32 v[90:91], v[46:47]
	v_mov_b64_e32 v[86:87], v[34:35]
	v_mov_b64_e32 v[82:83], v[38:39]
	v_mov_b32_e32 v11, v105
	v_mov_b32_e32 v12, v105
	v_mov_b32_e32 v13, v105
	v_mov_b32_e32 v14, v105
	v_mov_b32_e32 v15, v105
	v_mov_b64_e32 v[88:89], v[44:45]
	v_mov_b64_e32 v[92:93], v[40:41]
	v_mov_b64_e32 v[80:81], v[36:37]
	v_mov_b64_e32 v[84:85], v[32:33]
	v_readlane_b32 s13, v254, 15
	v_readlane_b32 s14, v254, 16
	v_readlane_b32 s15, v254, 17
	v_readlane_b32 s16, v254, 18
	v_readlane_b32 s17, v254, 19
	v_readlane_b32 s18, v254, 20
	v_readlane_b32 s19, v254, 21
	v_readlane_b32 s22, v254, 24
	v_readlane_b32 s23, v254, 25
	v_readlane_b32 s24, v254, 26
	v_readlane_b32 s25, v254, 27
	v_readlane_b32 s26, v254, 28
	v_readlane_b32 s27, v254, 29
	s_cmpk_eq_i32 s5, 0xc0
	s_cbranch_scc1 .LBB0_239
	s_branch .LBB0_238

.LBB0_459:
	s_mov_b64 s[0:1], exec
	v_readlane_b32 s4, v252, 3
	v_readlane_b32 s5, v252, 4
	s_and_b64 s[4:5], s[0:1], s[4:5]
	s_xor_b64 s[0:1], s[4:5], s[0:1]
	s_mov_b64 exec, s[4:5]
	s_cbranch_execz .LBB0_228
	s_mov_b64 s[4:5], exec
	v_mbcnt_lo_u32_b32 v0, s4, 0
	v_mbcnt_hi_u32_b32 v0, s5, v0
	v_cmp_eq_u32_e32 vcc, 0, v0
	s_and_saveexec_b64 s[6:7], vcc
	s_cbranch_execz .LBB0_227
	s_waitcnt vmcnt(0)
	v_cmp_eq_u32_e32 vcc, 1, v249
	s_cbranch_vccnz .Lclaim_have
	s_bcnt1_i32_b64 s4, s[4:5]
	v_mov_b32_e32 v1, s4
	global_atomic_add v1, v129, v1, s[56:57] sc0
	s_branch .LBB0_227
.Lclaim_have:
	v_mov_b32_e32 v1, v250
	s_branch .LBB0_227
.Lclaim_hook_a0:
	v_readlane_b32 s8, v252, 3
	v_readlane_b32 s9, v252, 4
	s_mov_b64 s[10:11], exec
	s_and_b64 exec, exec, s[8:9]
	v_mov_b32_e32 v251, 1
	v_mov_b32_e32 v249, 1
	global_atomic_add v250, v129, v251, s[56:57] sc0
	s_mov_b64 exec, s[10:11]
	s_branch .LBB0_239
